# gla_step3 output staged through LDS and written as 4 row-contiguous dwordx4 stores instead of 32 short stores
# baseline (speedup 1.0000x reference)
; __device__ __forceinline__ unsigned f2bf(float f) { return pk2(f, 0.f) & 0xffffu; }
; __device__ __forceinline__ float bf2f(bf16 v) { return __uint_as_float(((unsigned)v) << 16); }
; __device__ __forceinline__ void gla_step3(const Params& P, int l, LAS unsigned char* lds, int item, int tid) {
;     ...
;     const float* gain = P.gla_norm_gain + l * 256; const float g0 = gain[e0 + i], g1 = gain[e0 + 16 + i];
;     bf16* mix = (bf16*)(P.ws + WS_XB);
; #pragma unroll
;     for (int ct = 0; ct < 4; ++ct)
; #pragma unroll
;         for (int j = 0; j < 4; ++j) { const int c = ct * 16 + quad * 4 + j;
;             const float r = PART[512 + c]; const size_t tt = (size_t)(t0 + c);
;             const float ga = bf2f(gra[ct][j]), gb = bf2f(grb[ct][j]);
;             mix[tt * 2048 + h * 256 + e0 + i] = (bf16)f2bf(acc[ct][0][j] * r * g0 * ga); mix[tt * 2048 + h * 256 + e0 + 16 + i] = (bf16)f2bf(acc[ct][1][j] * r * g1 * gb); }
.LBB0_633:
	s_or_b64 exec, exec, s[0:1]
	v_and_b32_e32 v120, 0x1c0, v234
	v_and_b32_e32 v121, 15, v234
	v_lshl_add_u32 v120, v121, 1, v120
	v_lshl_add_u64 v[52:53], v[56:57], 2, s[4:5]
	s_waitcnt lgkmcnt(0)
	s_barrier
	global_load_dword v57, v[52:53], off
	global_load_dword v56, v[52:53], off offset:64
	s_add_u32 s0, s44, s9
	s_addc_u32 s1, s45, 0
	v_mov_b32_e32 v122, s0
	v_mov_b32_e32 v123, s1
	v_lshl_add_u64 v[52:53], v[54:55], 1, s[0:1]
	v_readlane_b32 s0, v255, 20
	v_lshl_add_u64 v[52:53], v[52:53], 0, v[0:1]
	v_ashrrev_i32_e32 v65, 31, v64
	v_lshl_add_u32 v0, v35, 2, s0
	ds_read_b128 v[90:93], v0 offset:2048
	s_waitcnt vmcnt(33)
	v_lshlrev_b32_e32 v0, 16, v63
	v_and_b32_e32 v127, 0xffffffc0, v64
	v_and_b32_e32 v54, 63, v64
	v_mul_u32_u24_e32 v54, 0x210, v54
	v_add_u32_e32 v54, v54, v120
	s_waitcnt vmcnt(32)
	v_lshlrev_b32_e32 v41, 16, v89
	s_waitcnt lgkmcnt(0)
	v_mul_f32_e32 v30, v30, v90
	v_ashrrev_i32_e32 v63, 31, v62
	v_ashrrev_i32_e32 v61, 31, v60
	v_ashrrev_i32_e32 v59, 31, v58
	s_add_i32 s14, s14, s62
	s_add_i32 s12, s12, s49
	s_waitcnt vmcnt(1)
	v_mul_f32_e32 v30, v57, v30
	v_mul_f32_e32 v0, v30, v0
	v_cvt_pk_bf16_f32 v0, v0, s0
	ds_write_b16 v54, v0
	v_mul_f32_e32 v0, v26, v90
	s_waitcnt vmcnt(0)
	v_mul_f32_e32 v0, v56, v0
	v_mul_f32_e32 v0, v0, v41
	v_cvt_pk_bf16_f32 v0, v0, s0
	v_mul_f32_e32 v30, v31, v91
	ds_write_b16 v54, v0 offset:32
	s_waitcnt vmcnt(31)
	v_lshlrev_b32_e32 v0, 16, v87
	v_mul_f32_e32 v30, v57, v30
	v_mul_f32_e32 v0, v30, v0
	v_and_b32_e32 v30, 63, v62
	v_mul_u32_u24_e32 v30, 0x210, v30
	v_add_u32_e32 v30, v30, v120
	v_cvt_pk_bf16_f32 v0, v0, s0
	ds_write_b16 v30, v0
	v_mul_f32_e32 v0, v27, v91
	s_waitcnt vmcnt(30)
	v_lshlrev_b32_e32 v26, 16, v88
	v_mul_f32_e32 v0, v56, v0
	v_mul_f32_e32 v0, v0, v26
	v_cvt_pk_bf16_f32 v0, v0, s0
	v_mul_f32_e32 v26, v32, v92
	ds_write_b16 v30, v0 offset:32
	s_waitcnt vmcnt(29)
	v_lshlrev_b32_e32 v0, 16, v85
	v_mul_f32_e32 v26, v57, v26
	v_mul_f32_e32 v0, v26, v0
	v_and_b32_e32 v26, 63, v60
	v_mul_u32_u24_e32 v26, 0x210, v26
	v_add_u32_e32 v26, v26, v120
	v_cvt_pk_bf16_f32 v0, v0, s0
	ds_write_b16 v26, v0
	v_mul_f32_e32 v0, v28, v92
	s_waitcnt vmcnt(28)
	v_lshlrev_b32_e32 v30, 16, v86
	v_mul_f32_e32 v0, v56, v0
	v_mul_f32_e32 v0, v0, v30
	v_cvt_pk_bf16_f32 v0, v0, s0
	ds_write_b16 v26, v0 offset:32
	v_mul_f32_e32 v26, v33, v93
	s_waitcnt vmcnt(27)
	v_lshlrev_b32_e32 v0, 16, v83
	v_mul_f32_e32 v26, v57, v26
	v_mul_f32_e32 v0, v26, v0
	v_and_b32_e32 v26, 63, v58
	v_mul_u32_u24_e32 v26, 0x210, v26
	v_add_u32_e32 v26, v26, v120
	v_cvt_pk_bf16_f32 v0, v0, s0
	ds_write_b16 v26, v0
	v_mul_f32_e32 v0, v29, v93
	s_waitcnt vmcnt(26)
	v_lshlrev_b32_e32 v28, 16, v84
	v_mul_f32_e32 v0, v56, v0
	v_mul_f32_e32 v0, v0, v28
	v_cvt_pk_bf16_f32 v0, v0, s0
	ds_write_b16 v26, v0 offset:32
	v_or_b32_e32 v0, 16, v35
	v_lshl_add_u32 v26, v0, 2, s0
	ds_read_b128 v[26:29], v26 offset:2048
	v_or_b32_e32 v30, s8, v0
	v_ashrrev_i32_e32 v31, 31, v30
	s_waitcnt vmcnt(25)
	v_lshlrev_b32_e32 v0, 16, v81
	v_and_b32_e32 v30, 63, v30
	v_mul_u32_u24_e32 v30, 0x210, v30
	v_add_u32_e32 v30, v30, v120
	s_waitcnt lgkmcnt(0)
	v_mul_f32_e32 v22, v22, v26
	v_mul_f32_e32 v22, v57, v22
	v_mul_f32_e32 v0, v22, v0
	v_cvt_pk_bf16_f32 v0, v0, s0
	ds_write_b16 v30, v0
	v_mul_f32_e32 v0, v18, v26
	s_waitcnt vmcnt(24)
	v_lshlrev_b32_e32 v32, 16, v82
	v_mul_f32_e32 v0, v56, v0
	v_mul_f32_e32 v0, v0, v32
	v_cvt_pk_bf16_f32 v0, v0, s0
	v_mul_f32_e32 v22, v23, v27
	ds_write_b16 v30, v0 offset:32
	v_ashrrev_i32_e32 v41, 31, v40
	s_waitcnt vmcnt(23)
	v_lshlrev_b32_e32 v0, 16, v43
	v_mul_f32_e32 v22, v57, v22
	v_mul_f32_e32 v0, v22, v0
	v_and_b32_e32 v22, 63, v40
	v_mul_u32_u24_e32 v22, 0x210, v22
	v_add_u32_e32 v22, v22, v120
	v_cvt_pk_bf16_f32 v0, v0, s0
	ds_write_b16 v22, v0
	v_mul_f32_e32 v0, v19, v27
	s_waitcnt vmcnt(22)
	v_lshlrev_b32_e32 v18, 16, v45
	v_mul_f32_e32 v0, v56, v0
	v_mul_f32_e32 v0, v0, v18
	v_cvt_pk_bf16_f32 v0, v0, s0
	v_mul_f32_e32 v18, v24, v28
	ds_write_b16 v22, v0 offset:32
	v_ashrrev_i32_e32 v43, 31, v42
	s_waitcnt vmcnt(21)
	v_lshlrev_b32_e32 v0, 16, v47
	v_mul_f32_e32 v18, v57, v18
	v_mul_f32_e32 v0, v18, v0
	v_and_b32_e32 v18, 63, v42
	v_mul_u32_u24_e32 v18, 0x210, v18
	v_add_u32_e32 v18, v18, v120
	v_cvt_pk_bf16_f32 v0, v0, s0
	ds_write_b16 v18, v0
	v_mul_f32_e32 v0, v20, v28
	s_waitcnt vmcnt(20)
	v_lshlrev_b32_e32 v22, 16, v49
	v_mul_f32_e32 v0, v56, v0
	v_mul_f32_e32 v0, v0, v22
	v_cvt_pk_bf16_f32 v0, v0, s0
	ds_write_b16 v18, v0 offset:32
	v_mul_f32_e32 v18, v25, v29
	v_ashrrev_i32_e32 v45, 31, v44
	s_waitcnt vmcnt(19)
	v_lshlrev_b32_e32 v0, 16, v75
	v_mul_f32_e32 v18, v57, v18
	v_mul_f32_e32 v0, v18, v0
	v_and_b32_e32 v18, 63, v44
	v_mul_u32_u24_e32 v18, 0x210, v18
	v_add_u32_e32 v18, v18, v120
	v_cvt_pk_bf16_f32 v0, v0, s0
	ds_write_b16 v18, v0
	v_mul_f32_e32 v0, v21, v29
	s_waitcnt vmcnt(18)
	v_lshlrev_b32_e32 v20, 16, v76
	v_mul_f32_e32 v0, v56, v0
	v_mul_f32_e32 v0, v0, v20
	v_cvt_pk_bf16_f32 v0, v0, s0
	ds_write_b16 v18, v0 offset:32
	v_or_b32_e32 v0, 32, v35
	v_lshl_add_u32 v18, v0, 2, s0
	ds_read_b128 v[18:21], v18 offset:2048
	v_or_b32_e32 v22, s8, v0
	v_ashrrev_i32_e32 v23, 31, v22
	s_waitcnt vmcnt(17)
	v_lshlrev_b32_e32 v0, 16, v51
	v_and_b32_e32 v22, 63, v22
	v_mul_u32_u24_e32 v22, 0x210, v22
	v_add_u32_e32 v22, v22, v120
	s_waitcnt lgkmcnt(0)
; __device__ __forceinline__ unsigned f2bf(float f) { return pk2(f, 0.f) & 0xffffu; }
; __device__ __forceinline__ float bf2f(bf16 v) { return __uint_as_float(((unsigned)v) << 16); }
; __device__ __forceinline__ void gla_step3(const Params& P, int l, LAS unsigned char* lds, int item, int tid) {
;     ...
; #pragma unroll
;     for (int ct = 0; ct < 4; ++ct)
; #pragma unroll
;         for (int j = 0; j < 4; ++j) { const int c = ct * 16 + quad * 4 + j;
;             const float r = PART[512 + c]; const size_t tt = (size_t)(t0 + c);
;             const float ga = bf2f(gra[ct][j]), gb = bf2f(grb[ct][j]);
;             mix[tt * 2048 + h * 256 + e0 + i] = (bf16)f2bf(acc[ct][0][j] * r * g0 * ga); mix[tt * 2048 + h * 256 + e0 + 16 + i] = (bf16)f2bf(acc[ct][1][j] * r * g1 * gb); }
	v_mul_f32_e32 v14, v14, v18
	v_mul_f32_e32 v14, v57, v14
	v_mul_f32_e32 v0, v14, v0
	v_cvt_pk_bf16_f32 v0, v0, s0
	ds_write_b16 v22, v0
	v_mul_f32_e32 v0, v10, v18
	s_waitcnt vmcnt(16)
	v_lshlrev_b32_e32 v24, 16, v72
	v_mul_f32_e32 v0, v56, v0
	v_mul_f32_e32 v0, v0, v24
	v_cvt_pk_bf16_f32 v0, v0, s0
	v_mul_f32_e32 v14, v15, v19
	ds_write_b16 v22, v0 offset:32
	v_ashrrev_i32_e32 v47, 31, v46
	s_waitcnt vmcnt(15)
	v_lshlrev_b32_e32 v0, 16, v73
	v_mul_f32_e32 v14, v57, v14
	v_mul_f32_e32 v0, v14, v0
	v_and_b32_e32 v14, 63, v46
	v_mul_u32_u24_e32 v14, 0x210, v14
	v_add_u32_e32 v14, v14, v120
	v_cvt_pk_bf16_f32 v0, v0, s0
	ds_write_b16 v14, v0
	v_mul_f32_e32 v0, v11, v19
	s_waitcnt vmcnt(14)
	v_lshlrev_b32_e32 v10, 16, v74
	v_mul_f32_e32 v0, v56, v0
	v_mul_f32_e32 v0, v0, v10
	v_cvt_pk_bf16_f32 v0, v0, s0
	v_mul_f32_e32 v10, v16, v20
	ds_write_b16 v14, v0 offset:32
	v_ashrrev_i32_e32 v49, 31, v48
	s_waitcnt vmcnt(13)
	v_lshlrev_b32_e32 v0, 16, v77
	v_mul_f32_e32 v10, v57, v10
	v_mul_f32_e32 v0, v10, v0
	v_and_b32_e32 v10, 63, v48
	v_mul_u32_u24_e32 v10, 0x210, v10
	v_add_u32_e32 v10, v10, v120
	v_cvt_pk_bf16_f32 v0, v0, s0
	ds_write_b16 v10, v0
	v_mul_f32_e32 v0, v12, v20
	s_waitcnt vmcnt(12)
	v_lshlrev_b32_e32 v14, 16, v78
	v_mul_f32_e32 v0, v56, v0
	v_mul_f32_e32 v0, v0, v14
	v_cvt_pk_bf16_f32 v0, v0, s0
	ds_write_b16 v10, v0 offset:32
	v_mul_f32_e32 v10, v17, v21
	v_ashrrev_i32_e32 v51, 31, v50
	s_waitcnt vmcnt(11)
	v_lshlrev_b32_e32 v0, 16, v79
	v_mul_f32_e32 v10, v57, v10
	v_mul_f32_e32 v0, v10, v0
	v_and_b32_e32 v10, 63, v50
	v_mul_u32_u24_e32 v10, 0x210, v10
	v_add_u32_e32 v10, v10, v120
	v_cvt_pk_bf16_f32 v0, v0, s0
	ds_write_b16 v10, v0
	v_mul_f32_e32 v0, v13, v21
	s_waitcnt vmcnt(10)
	v_lshlrev_b32_e32 v12, 16, v80
	v_mul_f32_e32 v0, v56, v0
	v_mul_f32_e32 v0, v0, v12
	v_cvt_pk_bf16_f32 v0, v0, s0
	ds_write_b16 v10, v0 offset:32
	v_or_b32_e32 v0, 48, v35
	v_lshl_add_u32 v10, v0, 2, s0
	ds_read_b128 v[10:13], v10 offset:2048
	v_or_b32_e32 v14, s8, v0
	v_ashrrev_i32_e32 v15, 31, v14
	s_waitcnt vmcnt(9)
	v_lshlrev_b32_e32 v0, 16, v37
	v_and_b32_e32 v14, 63, v14
	v_mul_u32_u24_e32 v14, 0x210, v14
	v_add_u32_e32 v14, v14, v120
	s_waitcnt lgkmcnt(0)
	v_mul_f32_e32 v6, v6, v10
	v_mul_f32_e32 v6, v57, v6
	v_mul_f32_e32 v0, v6, v0
	v_cvt_pk_bf16_f32 v0, v0, s0
	ds_write_b16 v14, v0
	v_mul_f32_e32 v0, v2, v10
	s_waitcnt vmcnt(8)
	v_lshlrev_b32_e32 v16, 16, v39
	v_mul_f32_e32 v0, v56, v0
	v_mul_f32_e32 v0, v0, v16
	v_cvt_pk_bf16_f32 v0, v0, s0
	v_mul_f32_e32 v6, v7, v11
	ds_write_b16 v14, v0 offset:32
	v_ashrrev_i32_e32 v35, 31, v34
	s_waitcnt vmcnt(7)
	v_lshlrev_b32_e32 v0, 16, v68
	v_mul_f32_e32 v6, v57, v6
	v_mul_f32_e32 v0, v6, v0
	v_and_b32_e32 v6, 63, v34
	v_mul_u32_u24_e32 v6, 0x210, v6
	v_add_u32_e32 v6, v6, v120
	v_cvt_pk_bf16_f32 v0, v0, s0
	ds_write_b16 v6, v0
	v_mul_f32_e32 v0, v3, v11
	s_waitcnt vmcnt(6)
	v_lshlrev_b32_e32 v2, 16, v69
	v_mul_f32_e32 v0, v56, v0
	v_mul_f32_e32 v0, v0, v2
	v_cvt_pk_bf16_f32 v0, v0, s0
	v_mul_f32_e32 v2, v8, v12
	ds_write_b16 v6, v0 offset:32
	v_ashrrev_i32_e32 v37, 31, v36
	s_waitcnt vmcnt(5)
	v_lshlrev_b32_e32 v0, 16, v70
	v_mul_f32_e32 v2, v57, v2
	v_mul_f32_e32 v0, v2, v0
	v_and_b32_e32 v2, 63, v36
	v_mul_u32_u24_e32 v2, 0x210, v2
	v_add_u32_e32 v2, v2, v120
	v_cvt_pk_bf16_f32 v0, v0, s0
	ds_write_b16 v2, v0
	v_mul_f32_e32 v0, v4, v12
	s_waitcnt vmcnt(4)
	v_lshlrev_b32_e32 v6, 16, v71
	v_mul_f32_e32 v0, v56, v0
	v_mul_f32_e32 v0, v0, v6
	v_cvt_pk_bf16_f32 v0, v0, s0
	ds_write_b16 v2, v0 offset:32
	v_mul_f32_e32 v2, v9, v13
	v_ashrrev_i32_e32 v39, 31, v38
	s_waitcnt vmcnt(3)
	v_lshlrev_b32_e32 v0, 16, v66
	v_mul_f32_e32 v2, v57, v2
	v_mul_f32_e32 v0, v2, v0
	v_and_b32_e32 v2, 63, v38
	v_mul_u32_u24_e32 v2, 0x210, v2
	v_add_u32_e32 v2, v2, v120
	v_cvt_pk_bf16_f32 v0, v0, s0
	ds_write_b16 v2, v0
	v_mul_f32_e32 v0, v5, v13
	s_waitcnt vmcnt(2)
	v_lshlrev_b32_e32 v4, 16, v67
	v_mul_f32_e32 v0, v56, v0
	v_mul_f32_e32 v0, v0, v4
	v_cvt_pk_bf16_f32 v0, v0, s0
	v_readlane_b32 s0, v254, 58
	s_add_i32 s13, s13, s0
	v_readlane_b32 s0, v254, 61
	v_readlane_b32 s1, v254, 62
	s_add_u32 s6, s6, s0
	s_addc_u32 s7, s7, s1
	ds_write_b16 v2, v0 offset:32
	s_waitcnt lgkmcnt(0)
	s_barrier
	v_lshrrev_b32_e32 v124, 5, v234
	v_and_b32_e32 v125, 31, v234
	v_mul_u32_u24_e32 v126, 0x210, v124
	v_lshl_add_u32 v126, v125, 4, v126
	ds_read_b128 v[128:131], v126
	ds_read_b128 v[132:135], v126 offset:8448
	ds_read_b128 v[136:139], v126 offset:16896
	ds_read_b128 v[140:143], v126 offset:25344
	v_add_u32_e32 v124, v127, v124
	v_mov_b32_e32 v125, 0
	v_lshlrev_b64 v[124:125], 12, v[124:125]
	v_lshl_add_u64 v[124:125], v[124:125], 0, v[122:123]
	v_and_b32_e32 v126, 31, v234
	v_lshlrev_b32_e32 v126, 4, v126
	v_mov_b32_e32 v127, 0
	v_lshl_add_u64 v[124:125], v[124:125], 0, v[126:127]
	s_mov_b32 s0, 0x10000
	s_mov_b32 s1, 0
	s_waitcnt lgkmcnt(3)
	global_store_dwordx4 v[124:125], v[128:131], off
	v_lshl_add_u64 v[124:125], v[124:125], 0, s[0:1]
	s_waitcnt lgkmcnt(2)
	global_store_dwordx4 v[124:125], v[132:135], off
	v_lshl_add_u64 v[124:125], v[124:125], 0, s[0:1]
	s_waitcnt lgkmcnt(1)
	global_store_dwordx4 v[124:125], v[136:139], off
	v_lshl_add_u64 v[124:125], v[124:125], 0, s[0:1]
	s_waitcnt lgkmcnt(0)
	global_store_dwordx4 v[124:125], v[140:143], off
	s_cmpk_gt_i32 s14, 0x3ff
	s_cbranch_scc1 .LBB0_676
